# prompt attention: counted vmcnt waits so the K/V prefetch is not drained by the QK block (plus Fdn1 tail move)
# baseline (speedup 1.0000x reference)
.LBB0_78:
	s_or_b64 exec, exec, s[0:1]
	s_lshl_b32 s0, s19, 2
	s_ashr_i32 s7, s19, 8
	s_and_b32 s21, s0, 60
	s_add_i32 s22, s21, s18
	s_lshl_b32 s0, s7, 12
	s_lshl_b32 s10, s22, 6
	s_ashr_i32 s1, s0, 31
	s_add_i32 s11, s10, s0
	s_or_b32 s23, s21, 3
	s_lshl_b64 s[0:1], s[0:1], 12
	s_add_u32 s0, s2, s0
	s_addc_u32 s1, s3, s1
	s_lshl_b32 s20, s6, 7
	s_lshl_b32 s88, s6, 8
	s_add_u32 s0, s0, s88
	v_sub_u32_e64 v14, s21, 8 clamp
	s_addc_u32 s1, s1, 0
	s_lshl_b32 s7, s7, 4
	s_or_b32 s6, s7, s6
	v_lshl_add_u32 v2, v14, 6, v168
	s_ashr_i32 s7, s6, 31
	v_ashrrev_i32_e32 v3, 31, v2
	s_lshl_b64 s[6:7], s[6:7], 20
	v_readlane_b32 s12, v245, 54
	v_lshlrev_b64 v[4:5], 12, v[2:3]
	s_add_u32 s6, s12, s6
	v_readlane_b32 s12, v245, 55
	v_lshl_add_u64 v[4:5], s[0:1], 0, v[4:5]
	s_addc_u32 s7, s12, s7
	v_lshl_add_u64 v[4:5], v[4:5], 0, v[0:1]
	s_mov_b32 s12, 0x20000
	v_add_u32_e32 v2, 64, v2
	v_add_co_u32_e32 v6, vcc, s12, v4
	v_ashrrev_i32_e32 v3, 31, v2
	s_nop 0
	v_addc_co_u32_e32 v7, vcc, 0, v5, vcc
	v_lshlrev_b64 v[2:3], 12, v[2:3]
	global_load_dwordx4 v[82:85], v[4:5], off
	global_load_dwordx4 v[86:89], v[6:7], off
	v_lshl_add_u64 v[4:5], s[6:7], 0, v[146:147]
	v_lshlrev_b32_e32 v6, 7, v14
	v_mov_b32_e32 v7, v1
	v_lshl_add_u64 v[10:11], s[6:7], 0, v[150:151]
	v_lshl_add_u64 v[2:3], s[0:1], 0, v[2:3]
	v_lshl_add_u64 v[8:9], v[4:5], 0, v[6:7]
	v_mov_b32_e32 v153, v1
	v_lshl_add_u64 v[6:7], v[10:11], 0, v[6:7]
	v_lshl_add_u64 v[2:3], v[2:3], 0, v[0:1]
	v_lshl_add_u64 v[8:9], v[8:9], 0, v[152:153]
	v_lshl_add_u64 v[6:7], v[6:7], 0, v[152:153]
	v_add_co_u32_e32 v12, vcc, s12, v2
	global_load_dwordx4 v[90:93], v[8:9], off
	global_load_dwordx4 v[94:97], v[6:7], off
	v_addc_co_u32_e32 v13, vcc, 0, v3, vcc
	global_load_dwordx4 v[98:101], v[2:3], off
	global_load_dwordx4 v[110:113], v[12:13], off
	global_load_dwordx4 v[138:141], v[8:9], off offset:128
	v_or_b32_e32 v2, s11, v169
	v_ashrrev_i32_e32 v3, 31, v2
	v_lshlrev_b64 v[8:9], 12, v[2:3]
	v_lshl_add_u64 v[8:9], s[46:47], 0, v[8:9]
	v_lshl_add_u64 v[8:9], v[8:9], 0, s[88:89]
	v_mov_b32_e32 v155, v1
	v_lshl_add_u64 v[8:9], v[8:9], 0, v[154:155]
	global_load_dwordx4 v[102:105], v[8:9], off
	global_load_dwordx4 v[106:109], v[8:9], off offset:32
	global_load_dwordx4 v[114:117], v[8:9], off offset:64
	global_load_dwordx4 v[118:121], v[8:9], off offset:96
	global_load_dwordx4 v[122:125], v[8:9], off offset:128
	global_load_dwordx4 v[126:129], v[8:9], off offset:160
	global_load_dwordx4 v[130:133], v[8:9], off offset:192
	global_load_dwordx4 v[134:137], v[8:9], off offset:224
	global_load_dwordx4 v[142:145], v[6:7], off offset:128
	v_mov_b32_e32 v6, s66
	v_mov_b32_e32 v50, v1
	v_mov_b32_e32 v51, v1
	v_mov_b32_e32 v52, v1
	v_mov_b32_e32 v53, v1
	v_mov_b32_e32 v54, v1
	v_mov_b32_e32 v55, v1
	v_mov_b32_e32 v56, v1
	v_mov_b32_e32 v57, v1
	v_mov_b32_e32 v58, v1
	v_readfirstlane_b32 s31, v14
	v_lshlrev_b64 v[158:159], 11, v[2:3]
	v_lshl_add_u64 v[162:163], v[4:5], 0, v[152:153]
	v_lshl_add_u64 v[164:165], v[10:11], 0, v[152:153]
	v_mov_b32_e32 v59, v1
	v_mov_b32_e32 v60, v1
	v_mov_b32_e32 v61, v1
	v_mov_b32_e32 v62, v1
	v_mov_b32_e32 v63, v1
	v_mov_b32_e32 v64, v1
	v_mov_b32_e32 v65, v1
	v_mov_b64_e32 v[34:35], v[50:51]
	v_mov_b64_e32 v[18:19], v[50:51]
	s_mov_b32 s50, 0x20000
	v_or_b32_e32 v155, s10, v169
	v_lshl_add_u64 v[160:161], s[0:1], 0, v[0:1]
	s_add_i32 s26, s22, -8
	v_mov_b32_e32 v182, 0xf149f2ca
	v_mov_b32_e32 v153, 0
	v_mov_b64_e32 v[36:37], v[52:53]
	v_mov_b64_e32 v[38:39], v[54:55]
	v_mov_b64_e32 v[40:41], v[56:57]
	s_waitcnt vmcnt(15)
	ds_write_b128 v173, v[82:85]
	s_waitcnt vmcnt(14)
	ds_write_b128 v173, v[86:89] offset:8704
	s_waitcnt vmcnt(13)
	ds_write_b128 v174, v[90:93] offset:17408
	s_waitcnt vmcnt(12)
	ds_write_b128 v175, v[94:97] offset:17408
	s_waitcnt lgkmcnt(0)
	s_barrier
	s_waitcnt vmcnt(1)
	ds_read_b32 v157, v6
	v_mov_b64_e32 v[2:3], v[50:51]
	v_mov_b64_e32 v[42:43], v[58:59]
	v_mov_b64_e32 v[44:45], v[60:61]
	v_mov_b64_e32 v[46:47], v[62:63]
	v_mov_b64_e32 v[48:49], v[64:65]
	v_mov_b64_e32 v[20:21], v[52:53]
	v_mov_b64_e32 v[22:23], v[54:55]
	v_mov_b64_e32 v[24:25], v[56:57]
	v_mov_b64_e32 v[26:27], v[58:59]
	v_mov_b64_e32 v[28:29], v[60:61]
	v_mov_b64_e32 v[30:31], v[62:63]
	v_mov_b64_e32 v[32:33], v[64:65]
	v_mov_b64_e32 v[4:5], v[52:53]
	v_mov_b64_e32 v[6:7], v[54:55]
	v_mov_b64_e32 v[8:9], v[56:57]
	v_mov_b64_e32 v[10:11], v[58:59]
	v_mov_b64_e32 v[12:13], v[60:61]
	v_mov_b64_e32 v[14:15], v[62:63]
	v_mov_b64_e32 v[16:17], v[64:65]

.LBB0_84:
	v_or_b32_e32 v66, s33, v149
	v_mad_u32_u24 v188, v66, s97, v176
	ds_read_b128 v[66:69], v188
	ds_read_b128 v[184:187], v188 offset:32
	s_waitcnt lgkmcnt(1)
	v_mfma_f32_32x32x16_bf16 v[66:81], v[66:69], v[102:105], 0
	ds_read_b128 v[192:195], v188 offset:224
	s_waitcnt lgkmcnt(1)
	v_mfma_f32_32x32x16_bf16 v[66:81], v[184:187], v[106:109], v[66:81]
	ds_read_b128 v[184:187], v188 offset:64
	s_waitcnt lgkmcnt(0)
	v_mfma_f32_32x32x16_bf16 v[66:81], v[184:187], v[114:117], v[66:81]
	ds_read_b128 v[184:187], v188 offset:96
	s_waitcnt lgkmcnt(0)
	v_mfma_f32_32x32x16_bf16 v[66:81], v[184:187], v[118:121], v[66:81]
	ds_read_b128 v[184:187], v188 offset:128
	s_waitcnt lgkmcnt(0)
	v_mfma_f32_32x32x16_bf16 v[66:81], v[184:187], v[122:125], v[66:81]
	ds_read_b128 v[184:187], v188 offset:160
	s_waitcnt lgkmcnt(0)
	v_mfma_f32_32x32x16_bf16 v[66:81], v[184:187], v[126:129], v[66:81]
	ds_read_b128 v[184:187], v188 offset:192
	s_waitcnt lgkmcnt(0)
	v_mfma_f32_32x32x16_bf16 v[66:81], v[184:187], v[130:133], v[66:81]
	v_add_u32_e32 v184, s33, v183
	v_cmp_gt_i32_e32 vcc, s61, v184
	v_cmp_lt_i32_e64 s[0:1], s64, v184
	v_mfma_f32_32x32x16_bf16 v[66:81], v[192:195], v[134:137], v[66:81]
	s_and_saveexec_b64 s[14:15], s[0:1]
	s_cbranch_execz .LBB0_86
	v_add_u32_e32 v184, v184, v148
	v_med3_i32 v185, v184, s39, 63
	v_lshl_add_u32 v188, v185, 2, s66
	v_add_u32_e32 v185, 1, v184
	v_med3_i32 v185, v185, s39, 63
	v_lshl_add_u32 v190, v185, 2, s66
	v_add_u32_e32 v185, 2, v184
	v_med3_i32 v185, v185, s39, 63
	v_lshl_add_u32 v198, v185, 2, s66
	v_add_u32_e32 v185, 3, v184
	v_med3_i32 v185, v185, s39, 63
	v_lshl_add_u32 v199, v185, 2, s66
	v_add_u32_e32 v185, 8, v184
	v_med3_i32 v185, v185, s39, 63
	v_lshl_add_u32 v200, v185, 2, s66
	v_add_u32_e32 v185, 9, v184
	v_med3_i32 v185, v185, s39, 63
	v_lshl_add_u32 v201, v185, 2, s66
	v_add_u32_e32 v185, 10, v184
	v_med3_i32 v185, v185, s39, 63
	v_lshl_add_u32 v202, v185, 2, s66
	v_add_u32_e32 v185, 11, v184
	v_med3_i32 v185, v185, s39, 63
	v_lshl_add_u32 v203, v185, 2, s66
	v_add_u32_e32 v185, 16, v184
	v_add_u32_e32 v186, 17, v184
	v_add_u32_e32 v187, 18, v184
	v_add_u32_e32 v192, 19, v184
	v_add_u32_e32 v193, 24, v184
	v_add_u32_e32 v194, 25, v184
	v_add_u32_e32 v195, 26, v184
	v_add_u32_e32 v184, 27, v184
	v_med3_i32 v185, v185, s39, 63
	v_med3_i32 v186, v186, s39, 63
	v_med3_i32 v187, v187, s39, 63
	v_med3_i32 v192, v192, s39, 63
	v_med3_i32 v193, v193, s39, 63
	v_med3_i32 v194, v194, s39, 63
	v_med3_i32 v195, v195, s39, 63
	v_med3_i32 v184, v184, s39, 63
	v_lshl_add_u32 v185, v185, 2, s66
	v_lshl_add_u32 v186, v186, 2, s66
	v_lshl_add_u32 v187, v187, 2, s66
	v_lshl_add_u32 v192, v192, 2, s66
	v_lshl_add_u32 v193, v193, 2, s66
	v_lshl_add_u32 v194, v194, 2, s66
	v_lshl_add_u32 v195, v195, 2, s66
	v_lshl_add_u32 v196, v184, 2, s66
	ds_read_b32 v184, v185 offset:512
	ds_read_b32 v185, v186 offset:512
	ds_read_b32 v186, v187 offset:512
	ds_read_b32 v187, v192 offset:512
	ds_read_b32 v192, v193 offset:512
	ds_read_b32 v193, v194 offset:512
	ds_read_b32 v194, v195 offset:512
	ds_read_b32 v195, v196 offset:512
	ds_read_b32 v196, v188 offset:512
	ds_read_b32 v197, v190 offset:512
	ds_read_b32 v198, v198 offset:512
	ds_read_b32 v199, v199 offset:512
	ds_read_b32 v200, v200 offset:512
	ds_read_b32 v201, v201 offset:512
	ds_read_b32 v202, v202 offset:512
	ds_read_b32 v203, v203 offset:512
	s_waitcnt lgkmcnt(8)
	v_pk_add_f32 v[80:81], v[80:81], v[194:195]
	v_pk_add_f32 v[78:79], v[78:79], v[192:193]
	v_pk_add_f32 v[76:77], v[76:77], v[186:187]
	v_pk_add_f32 v[74:75], v[74:75], v[184:185]
	s_waitcnt lgkmcnt(0)
	v_pk_add_f32 v[72:73], v[72:73], v[202:203]
	v_pk_add_f32 v[70:71], v[70:71], v[200:201]
	v_pk_add_f32 v[68:69], v[68:69], v[198:199]
	v_pk_add_f32 v[66:67], v[66:67], v[196:197]

.LBB0_88:
	s_and_b64 vcc, exec, s[10:11]
	s_cbranch_vccz .Lpa_w88_all
	s_waitcnt vmcnt(4)
	s_branch .Lpa_w88_done

.Lpa_w88_done:
	s_cmp_gt_u32 s31, s21
	ds_write_b128 v173, v[98:101] offset:35840
	ds_write_b128 v173, v[110:113] offset:44544
	ds_write_b128 v174, v[138:141] offset:53248
	ds_write_b128 v175, v[142:145] offset:53248
	s_waitcnt lgkmcnt(0)
	s_barrier
	s_cbranch_scc1 .LBB0_90
	v_lshl_add_u32 v66, s31, 6, v181
	v_ashrrev_i32_e32 v67, 31, v66
	v_lshlrev_b64 v[66:67], 12, v[66:67]
	v_lshl_add_u64 v[66:67], v[160:161], 0, v[66:67]
	v_add_co_u32_e32 v68, vcc, 0x20000, v66
	s_lshl_b32 s88, s31, 7
	s_nop 0
	v_addc_co_u32_e32 v69, vcc, 0, v67, vcc
	global_load_dwordx4 v[98:101], v[66:67], off
	global_load_dwordx4 v[110:113], v[68:69], off
	v_lshl_add_u64 v[66:67], v[162:163], 0, s[88:89]
	v_lshl_add_u64 v[68:69], v[164:165], 0, s[88:89]
	global_load_dwordx4 v[138:141], v[66:67], off offset:384
	global_load_dwordx4 v[142:145], v[68:69], off offset:384

.LBB0_97:
	s_andn2_b64 vcc, exec, s[10:11]
	s_cbranch_vccnz .LBB0_99
	s_waitcnt vmcnt(4)
	ds_write_b128 v173, v[82:85]
	ds_write_b128 v173, v[86:89] offset:8704
	ds_write_b128 v174, v[90:93] offset:17408
	ds_write_b128 v175, v[94:97] offset:17408
